# memory attention (layer 1): Q loads hoisted above the LDS staging, vmcnt waits recounted so the next unit's K/V prefetch stays in flight across the MFMA part
# speedup vs baseline: 1.0058x; 1.0058x over previous
.LBB0_577:
	ds_read_b128 v[44:47], v128
	ds_read_b128 v[48:51], v128 offset:64
	s_mov_b32 s13, 0xff61b1e6
	s_waitcnt vmcnt(11) lgkmcnt(1)
	v_mfma_f32_16x16x32_bf16 v[44:47], v[44:47], v[108:111], 0
	ds_read_b128 v[52:55], v128 offset:27712
	ds_read_b128 v[56:59], v128 offset:30016
	ds_read_b128 v[130:133], v128 offset:32320
	s_waitcnt vmcnt(10) lgkmcnt(3)
	v_mfma_f32_16x16x32_bf16 v[104:107], v[48:51], v[60:63], v[44:47]
	ds_read_b128 v[48:51], v128 offset:2368
	s_nop 1
	ds_read_b128 v[44:47], v128 offset:2304
	s_waitcnt lgkmcnt(0)
	v_mfma_f32_16x16x32_bf16 v[44:47], v[44:47], v[108:111], 0
	v_mfma_f32_16x16x32_bf16 v[100:103], v[48:51], v[60:63], v[44:47]
	ds_read_b128 v[48:51], v128 offset:4672
	s_nop 5
	ds_read_b128 v[44:47], v128 offset:4608
	s_waitcnt lgkmcnt(0)
	v_mfma_f32_16x16x32_bf16 v[44:47], v[44:47], v[108:111], 0
	v_mfma_f32_16x16x32_bf16 v[96:99], v[48:51], v[60:63], v[44:47]
	ds_read_b128 v[48:51], v128 offset:6976
	s_nop 5
	ds_read_b128 v[44:47], v128 offset:6912
	s_waitcnt lgkmcnt(0)
	v_mfma_f32_16x16x32_bf16 v[44:47], v[44:47], v[108:111], 0
	v_mfma_f32_16x16x32_bf16 v[92:95], v[48:51], v[60:63], v[44:47]
	ds_read_b128 v[48:51], v128 offset:9280
	s_nop 5
	ds_read_b128 v[44:47], v128 offset:9216
	s_waitcnt lgkmcnt(0)
	v_mfma_f32_16x16x32_bf16 v[44:47], v[44:47], v[108:111], 0
	v_mfma_f32_16x16x32_bf16 v[88:91], v[48:51], v[60:63], v[44:47]
	ds_read_b128 v[48:51], v128 offset:11584
	s_nop 5
	ds_read_b128 v[44:47], v128 offset:11520
	s_waitcnt lgkmcnt(0)
	v_mfma_f32_16x16x32_bf16 v[44:47], v[44:47], v[108:111], 0
	v_mfma_f32_16x16x32_bf16 v[84:87], v[48:51], v[60:63], v[44:47]
	ds_read_b128 v[48:51], v128 offset:13888
	s_nop 5
	ds_read_b128 v[44:47], v128 offset:13824
	s_waitcnt lgkmcnt(0)
	v_mfma_f32_16x16x32_bf16 v[44:47], v[44:47], v[108:111], 0
	v_mfma_f32_16x16x32_bf16 v[80:83], v[48:51], v[60:63], v[44:47]
	ds_read_b128 v[48:51], v128 offset:16192
	s_nop 5
	ds_read_b128 v[44:47], v128 offset:16128
	s_waitcnt lgkmcnt(0)
	v_mfma_f32_16x16x32_bf16 v[44:47], v[44:47], v[108:111], 0
	v_mfma_f32_16x16x32_bf16 v[76:79], v[48:51], v[60:63], v[44:47]
	ds_read_b128 v[48:51], v128 offset:18496
	s_nop 5
	ds_read_b128 v[44:47], v128 offset:18432
	s_waitcnt lgkmcnt(0)
	v_mfma_f32_16x16x32_bf16 v[44:47], v[44:47], v[108:111], 0
	v_mfma_f32_16x16x32_bf16 v[72:75], v[48:51], v[60:63], v[44:47]
	ds_read_b128 v[48:51], v128 offset:20800
	s_nop 5
	ds_read_b128 v[44:47], v128 offset:20736
	s_waitcnt lgkmcnt(0)
	v_mfma_f32_16x16x32_bf16 v[44:47], v[44:47], v[108:111], 0
	v_mfma_f32_16x16x32_bf16 v[68:71], v[48:51], v[60:63], v[44:47]
	ds_read_b128 v[48:51], v128 offset:23104
	s_nop 5
	ds_read_b128 v[44:47], v128 offset:23040
	s_waitcnt lgkmcnt(0)
	v_mfma_f32_16x16x32_bf16 v[44:47], v[44:47], v[108:111], 0
	v_mfma_f32_16x16x32_bf16 v[64:67], v[48:51], v[60:63], v[44:47]
	ds_read_b128 v[48:51], v128 offset:25408
	s_nop 5
	ds_read_b128 v[44:47], v128 offset:25344
	s_waitcnt lgkmcnt(0)
	v_mfma_f32_16x16x32_bf16 v[44:47], v[44:47], v[108:111], 0
	v_mfma_f32_16x16x32_bf16 v[44:47], v[48:51], v[60:63], v[44:47]
	ds_read_b128 v[48:51], v128 offset:27648
	s_waitcnt lgkmcnt(0)
	v_mfma_f32_16x16x32_bf16 v[48:51], v[48:51], v[108:111], 0
	v_mfma_f32_16x16x32_bf16 v[48:51], v[52:55], v[60:63], v[48:51]
	ds_read_b128 v[52:55], v128 offset:29952
	s_waitcnt lgkmcnt(0)
	v_mfma_f32_16x16x32_bf16 v[52:55], v[52:55], v[108:111], 0
	v_mfma_f32_16x16x32_bf16 v[52:55], v[56:59], v[60:63], v[52:55]
	ds_read_b128 v[56:59], v128 offset:32256
	s_waitcnt lgkmcnt(0)
	v_mfma_f32_16x16x32_bf16 v[56:59], v[56:59], v[108:111], 0
	v_mfma_f32_16x16x32_bf16 v[56:59], v[130:133], v[60:63], v[56:59]
	ds_read_b128 v[130:133], v128 offset:34560
	s_waitcnt lgkmcnt(0)
	v_mfma_f32_16x16x32_bf16 v[108:111], v[130:133], v[108:111], 0
	ds_read_b128 v[130:133], v128 offset:34624
	s_waitcnt lgkmcnt(0)
	v_mfma_f32_16x16x32_bf16 v[60:63], v[130:133], v[60:63], v[108:111]
	s_nop 4
	v_max_f32_e32 v108, v105, v105
	v_max_f32_e32 v109, v104, v104
	v_max_f32_e32 v108, v109, v108
	v_max_f32_e32 v109, v107, v107
	v_max_f32_e32 v110, v106, v106
	v_max_f32_e32 v109, v110, v109
	v_max3_f32 v108, v108, v109, s13
	v_max_f32_e32 v109, v101, v101
	v_max_f32_e32 v110, v100, v100
	v_max_f32_e32 v109, v110, v109
	v_max_f32_e32 v110, v103, v103
	v_max_f32_e32 v111, v102, v102
	v_max_f32_e32 v110, v111, v110
	v_max3_f32 v108, v109, v110, v108
	v_max_f32_e32 v109, v97, v97
	v_max_f32_e32 v110, v96, v96
	v_max_f32_e32 v109, v110, v109
	v_max_f32_e32 v110, v99, v99
	v_max_f32_e32 v111, v98, v98
	v_max_f32_e32 v110, v111, v110
	v_max3_f32 v108, v109, v110, v108
	v_max_f32_e32 v109, v93, v93
	v_max_f32_e32 v110, v92, v92
	v_max_f32_e32 v109, v110, v109
	v_max_f32_e32 v110, v95, v95
	v_max_f32_e32 v111, v94, v94
	v_max_f32_e32 v110, v111, v110
	v_max3_f32 v108, v109, v110, v108
	v_max_f32_e32 v109, v89, v89
	v_max_f32_e32 v110, v88, v88
	v_max_f32_e32 v109, v110, v109
	v_max_f32_e32 v110, v91, v91
	v_max_f32_e32 v111, v90, v90
	v_max_f32_e32 v110, v111, v110
	v_max3_f32 v108, v109, v110, v108
	v_max_f32_e32 v109, v85, v85
	v_max_f32_e32 v110, v84, v84
	v_max_f32_e32 v109, v110, v109
	v_max_f32_e32 v110, v87, v87
	v_max_f32_e32 v111, v86, v86
	v_max_f32_e32 v110, v111, v110
	v_max3_f32 v108, v109, v110, v108
	v_max_f32_e32 v109, v81, v81
	v_max_f32_e32 v110, v80, v80
	v_max_f32_e32 v109, v110, v109
	v_max_f32_e32 v110, v83, v83
	v_max_f32_e32 v111, v82, v82
	v_max_f32_e32 v110, v111, v110
	v_max3_f32 v108, v109, v110, v108
	v_max_f32_e32 v109, v77, v77
	v_max_f32_e32 v110, v76, v76
	v_max_f32_e32 v109, v110, v109
	v_max_f32_e32 v110, v79, v79
	v_max_f32_e32 v111, v78, v78
	v_max_f32_e32 v110, v111, v110
	v_max3_f32 v108, v109, v110, v108
	v_max_f32_e32 v109, v73, v73
	v_max_f32_e32 v110, v72, v72
	v_max_f32_e32 v109, v110, v109
	v_max_f32_e32 v110, v75, v75
	v_max_f32_e32 v111, v74, v74
	v_max_f32_e32 v110, v111, v110
	v_max3_f32 v108, v109, v110, v108
	v_max_f32_e32 v109, v69, v69
	v_max_f32_e32 v110, v68, v68
	v_max_f32_e32 v109, v110, v109
	v_max_f32_e32 v110, v71, v71
	v_max_f32_e32 v111, v70, v70
	v_max_f32_e32 v110, v111, v110
	v_max3_f32 v108, v109, v110, v108
	v_max_f32_e32 v109, v65, v65
	v_max_f32_e32 v110, v64, v64
	v_max_f32_e32 v109, v110, v109
	v_max_f32_e32 v110, v67, v67
	v_max_f32_e32 v111, v66, v66
	v_max_f32_e32 v110, v111, v110
	v_max3_f32 v108, v109, v110, v108
	v_max_f32_e32 v109, v45, v45
	v_max_f32_e32 v110, v44, v44
	v_max_f32_e32 v109, v110, v109
	v_max_f32_e32 v110, v47, v47
	v_max_f32_e32 v111, v46, v46
	v_max_f32_e32 v110, v111, v110
	v_max3_f32 v108, v109, v110, v108
	v_max_f32_e32 v109, v49, v49
	v_max_f32_e32 v110, v48, v48
	v_max_f32_e32 v109, v110, v109
	v_max_f32_e32 v110, v51, v51
	v_max_f32_e32 v111, v50, v50
	v_max_f32_e32 v110, v111, v110
	v_max3_f32 v108, v109, v110, v108
	v_max_f32_e32 v109, v53, v53
	v_max_f32_e32 v110, v52, v52
	v_max_f32_e32 v109, v110, v109
	v_max_f32_e32 v110, v55, v55
	v_max_f32_e32 v111, v54, v54
	v_max_f32_e32 v110, v111, v110
	v_max3_f32 v108, v109, v110, v108
	v_max_f32_e32 v109, v57, v57
	v_max_f32_e32 v110, v56, v56
	v_max_f32_e32 v109, v110, v109
	v_max_f32_e32 v110, v59, v59
	v_max_f32_e32 v111, v58, v58
	v_max_f32_e32 v110, v111, v110
	v_max3_f32 v108, v109, v110, v108
	v_max_f32_e32 v109, v61, v61
	v_max_f32_e32 v110, v60, v60
	v_max_f32_e32 v109, v110, v109
	v_max_f32_e32 v110, v63, v63
	v_max_f32_e32 v111, v62, v62
	v_max_f32_e32 v110, v111, v110
	v_max3_f32 v108, v109, v110, v108
	ds_bpermute_b32 v109, v126, v108
	s_waitcnt lgkmcnt(0)
	v_max_f32_e32 v109, v109, v109
	v_max_f32_e32 v108, v108, v109
	ds_bpermute_b32 v109, v127, v108
	s_waitcnt lgkmcnt(0)
	v_max_f32_e32 v109, v109, v109
	v_max_f32_e32 v133, v108, v109
	v_sub_f32_e32 v104, v104, v133
	v_exp_f32_e32 v104, v104
	v_sub_f32_e32 v105, v105, v133
	v_exp_f32_e32 v105, v105
	v_sub_f32_e32 v106, v106, v133
	v_exp_f32_e32 v106, v106
	v_sub_f32_e32 v107, v107, v133
	v_exp_f32_e32 v107, v107
	v_sub_f32_e32 v100, v100, v133
	v_add_f32_e32 v108, 0, v104
	v_exp_f32_e32 v110, v100
	v_sub_f32_e32 v101, v101, v133
	v_add_f32_e32 v108, v105, v108
	v_exp_f32_e32 v130, v101
	v_sub_f32_e32 v101, v102, v133
	v_add_f32_e32 v108, v106, v108
	v_exp_f32_e32 v131, v101
	v_sub_f32_e32 v101, v103, v133
	v_add_f32_e32 v108, v107, v108
	v_exp_f32_e32 v132, v101
	v_sub_f32_e32 v96, v96, v133
	v_add_f32_e32 v100, v110, v108
	v_exp_f32_e32 v96, v96
	v_sub_f32_e32 v97, v97, v133
	v_add_f32_e32 v100, v130, v100
	v_exp_f32_e32 v97, v97
	v_add_f32_e32 v100, v131, v100
	v_add_f32_e32 v100, v132, v100
	v_add_f32_e32 v100, v96, v100
	v_sub_f32_e32 v98, v98, v133
	v_add_f32_e32 v101, v97, v100
	v_exp_f32_e32 v100, v98
	v_sub_f32_e32 v99, v99, v133
	v_sub_f32_e32 v92, v92, v133
	v_exp_f32_e32 v103, v92
	v_add_f32_e32 v98, v100, v101
	v_exp_f32_e32 v101, v99
	v_sub_f32_e32 v93, v93, v133
	v_exp_f32_e32 v111, v93
	v_sub_f32_e32 v93, v94, v133
	v_exp_f32_e32 v113, v93
	v_sub_f32_e32 v93, v95, v133
	v_add_f32_e32 v98, v101, v98
	v_exp_f32_e32 v129, v93
	v_sub_f32_e32 v88, v88, v133
	v_add_f32_e32 v92, v103, v98
	v_exp_f32_e32 v88, v88
	v_sub_f32_e32 v89, v89, v133
	v_add_f32_e32 v92, v111, v92
	v_exp_f32_e32 v89, v89
	v_add_f32_e32 v92, v113, v92
	v_add_f32_e32 v92, v129, v92
	v_add_f32_e32 v92, v88, v92
	v_sub_f32_e32 v90, v90, v133
	v_add_f32_e32 v93, v89, v92
	v_exp_f32_e32 v92, v90
	v_sub_f32_e32 v91, v91, v133
	v_sub_f32_e32 v84, v84, v133
	v_exp_f32_e32 v95, v84
	v_add_f32_e32 v90, v92, v93
	v_exp_f32_e32 v93, v91
	v_sub_f32_e32 v85, v85, v133
	v_exp_f32_e32 v102, v85
	v_sub_f32_e32 v85, v86, v133
	v_exp_f32_e32 v108, v85
	v_sub_f32_e32 v85, v87, v133
	v_add_f32_e32 v90, v93, v90
	v_exp_f32_e32 v109, v85
	v_sub_f32_e32 v80, v80, v133
	v_add_f32_e32 v84, v95, v90
	v_exp_f32_e32 v80, v80
	v_sub_f32_e32 v81, v81, v133
	v_add_f32_e32 v84, v102, v84
	v_exp_f32_e32 v81, v81
	v_add_f32_e32 v84, v108, v84
	v_add_f32_e32 v84, v109, v84
	v_add_f32_e32 v84, v80, v84
	v_sub_f32_e32 v82, v82, v133
	v_add_f32_e32 v85, v81, v84
	v_exp_f32_e32 v84, v82
	v_sub_f32_e32 v83, v83, v133
	v_sub_f32_e32 v76, v76, v133
	v_exp_f32_e32 v87, v76
	v_add_f32_e32 v82, v84, v85
	v_exp_f32_e32 v85, v83
	v_sub_f32_e32 v77, v77, v133
	v_exp_f32_e32 v94, v77
	v_sub_f32_e32 v77, v78, v133
	v_exp_f32_e32 v98, v77
	v_sub_f32_e32 v77, v79, v133
	v_add_f32_e32 v82, v85, v82
	v_exp_f32_e32 v99, v77
	v_sub_f32_e32 v72, v72, v133
	v_add_f32_e32 v76, v87, v82
	v_exp_f32_e32 v72, v72
	v_add_f32_e32 v76, v94, v76
	v_add_f32_e32 v76, v98, v76
	v_add_f32_e32 v76, v99, v76
	v_sub_f32_e32 v73, v73, v133
	v_add_f32_e32 v77, v72, v76
	v_exp_f32_e32 v76, v73
	v_sub_f32_e32 v74, v74, v133
	v_sub_f32_e32 v68, v68, v133
	v_exp_f32_e32 v79, v68
	v_add_f32_e32 v73, v76, v77
	v_exp_f32_e32 v77, v74
	v_sub_f32_e32 v74, v75, v133
	v_exp_f32_e32 v75, v74
	v_sub_f32_e32 v69, v69, v133
	v_exp_f32_e32 v86, v69
	v_sub_f32_e32 v69, v70, v133
	v_add_f32_e32 v73, v77, v73
	v_exp_f32_e32 v90, v69
	v_sub_f32_e32 v69, v71, v133
	v_add_f32_e32 v73, v75, v73
	v_exp_f32_e32 v91, v69
	v_sub_f32_e32 v64, v64, v133
	v_add_f32_e32 v68, v79, v73
	v_exp_f32_e32 v69, v64
	v_sub_f32_e32 v65, v65, v133
	v_add_f32_e32 v68, v86, v68
	v_exp_f32_e32 v70, v65
	v_sub_f32_e32 v65, v66, v133
	v_add_f32_e32 v68, v90, v68
	v_exp_f32_e32 v71, v65
	v_sub_f32_e32 v65, v67, v133
	v_add_f32_e32 v68, v91, v68
	v_exp_f32_e32 v73, v65
	v_sub_f32_e32 v44, v44, v133
	v_add_f32_e32 v64, v69, v68
	v_exp_f32_e32 v74, v44
	v_sub_f32_e32 v45, v45, v133
	v_add_f32_e32 v64, v70, v64
	v_exp_f32_e32 v78, v45
	v_sub_f32_e32 v45, v46, v133
	v_add_f32_e32 v64, v71, v64
	v_exp_f32_e32 v82, v45
	v_sub_f32_e32 v45, v47, v133
	v_add_f32_e32 v64, v73, v64
	v_exp_f32_e32 v83, v45
	v_sub_f32_e32 v45, v48, v133
	v_add_f32_e32 v44, v74, v64
	v_exp_f32_e32 v64, v45
	v_sub_f32_e32 v45, v49, v133
	v_add_f32_e32 v44, v78, v44
	v_exp_f32_e32 v65, v45
	v_sub_f32_e32 v45, v50, v133
	v_add_f32_e32 v44, v82, v44
	v_exp_f32_e32 v66, v45
	v_sub_f32_e32 v45, v51, v133
	v_add_f32_e32 v44, v83, v44
	v_exp_f32_e32 v67, v45
	v_sub_f32_e32 v45, v52, v133
	v_add_f32_e32 v44, v64, v44
	v_exp_f32_e32 v68, v45
	v_sub_f32_e32 v45, v53, v133
	v_add_f32_e32 v44, v65, v44
	v_exp_f32_e32 v53, v45
	v_sub_f32_e32 v45, v54, v133
	v_add_f32_e32 v44, v66, v44
	v_exp_f32_e32 v54, v45
	v_sub_f32_e32 v45, v55, v133
	v_add_f32_e32 v44, v67, v44
	v_exp_f32_e32 v55, v45
	v_sub_f32_e32 v45, v56, v133
	v_add_f32_e32 v44, v68, v44
	v_exp_f32_e32 v45, v45
	v_sub_f32_e32 v46, v57, v133
	v_add_f32_e32 v44, v53, v44
	v_exp_f32_e32 v46, v46
	v_sub_f32_e32 v47, v58, v133
	v_add_f32_e32 v44, v54, v44
	v_exp_f32_e32 v47, v47
	v_sub_f32_e32 v48, v59, v133
	v_add_f32_e32 v44, v55, v44
	v_exp_f32_e32 v48, v48
	v_sub_f32_e32 v49, v60, v133
	v_add_f32_e32 v44, v45, v44
	v_exp_f32_e32 v49, v49
	v_sub_f32_e32 v50, v61, v133
	v_add_f32_e32 v44, v46, v44
	v_exp_f32_e32 v50, v50
	v_sub_f32_e32 v51, v62, v133
	v_add_f32_e32 v44, v47, v44
	v_exp_f32_e32 v51, v51
	v_sub_f32_e32 v52, v63, v133
	v_add_f32_e32 v44, v48, v44
	v_exp_f32_e32 v52, v52
	v_add_f32_e32 v44, v49, v44
	v_add_f32_e32 v44, v50, v44
	v_add_f32_e32 v44, v51, v44
	v_add_f32_e32 v44, v52, v44
	ds_bpermute_b32 v56, v126, v44
	s_waitcnt lgkmcnt(0)
	v_add_f32_e32 v44, v44, v56
	ds_bpermute_b32 v56, v127, v44
	s_waitcnt lgkmcnt(0)
	v_add_f32_e32 v44, v44, v56
	v_cvt_pk_bf16_f32 v56, v104, v105
	v_cvt_pk_bf16_f32 v57, v106, v107
	v_add_u32_e32 v105, 0x9000, v122
	v_add_u32_e32 v104, 0x9000, v123
	v_add_u32_e32 v107, 0x9000, v124
	v_add_u32_e32 v106, 0x9000, v125
	v_cvt_pk_bf16_f32 v58, v110, v130
	v_cvt_pk_bf16_f32 v59, v131, v132
	ds_read2_b64 v[60:63], v105 offset1:4
	ds_read2_b64 v[130:133], v104 offset1:4
	ds_read2_b64 v[134:137], v107 offset1:4
	ds_read2_b64 v[138:141], v106 offset1:4
	s_waitcnt lgkmcnt(3)
	v_mfma_f32_16x16x32_bf16 v[60:63], v[60:63], v[56:59], 0
	s_waitcnt lgkmcnt(2)
	v_mfma_f32_16x16x32_bf16 v[130:133], v[130:133], v[56:59], 0
	s_waitcnt lgkmcnt(1)
	v_mfma_f32_16x16x32_bf16 v[134:137], v[134:137], v[56:59], 0
	s_waitcnt lgkmcnt(0)
	v_mfma_f32_16x16x32_bf16 v[56:59], v[138:141], v[56:59], 0
	v_cvt_pk_bf16_f32 v138, v96, v97
	v_cvt_pk_bf16_f32 v139, v100, v101
	v_cvt_pk_bf16_f32 v140, v103, v111
	v_cvt_pk_bf16_f32 v141, v113, v129
	ds_read2_b64 v[142:145], v105 offset0:8 offset1:12
	s_waitcnt lgkmcnt(0)
	v_mfma_f32_16x16x32_bf16 v[60:63], v[142:145], v[138:141], v[60:63]
	ds_read2_b64 v[142:145], v104 offset0:8 offset1:12
	s_waitcnt lgkmcnt(0)
	v_mfma_f32_16x16x32_bf16 v[130:133], v[142:145], v[138:141], v[130:133]
	ds_read2_b64 v[142:145], v107 offset0:8 offset1:12
	s_waitcnt lgkmcnt(0)
	v_mfma_f32_16x16x32_bf16 v[134:137], v[142:145], v[138:141], v[134:137]
	ds_read2_b64 v[142:145], v106 offset0:8 offset1:12
	v_cvt_pk_bf16_f32 v100, v88, v89
	v_cvt_pk_bf16_f32 v101, v92, v93
	v_cvt_pk_bf16_f32 v102, v95, v102
	v_cvt_pk_bf16_f32 v103, v108, v109
	ds_read2_b64 v[108:111], v105 offset0:16 offset1:20
	s_waitcnt lgkmcnt(0)
	v_mfma_f32_16x16x32_bf16 v[60:63], v[108:111], v[100:103], v[60:63]
	ds_read2_b64 v[108:111], v104 offset0:16 offset1:20
	s_waitcnt lgkmcnt(0)
	v_mfma_f32_16x16x32_bf16 v[108:111], v[108:111], v[100:103], v[130:133]
	s_nop 2
	ds_read2_b64 v[130:133], v107 offset0:16 offset1:20
	s_waitcnt lgkmcnt(0)
	v_mfma_f32_16x16x32_bf16 v[130:133], v[130:133], v[100:103], v[134:137]
	s_nop 2
	ds_read2_b64 v[134:137], v106 offset0:16 offset1:20
	v_cvt_pk_bf16_f32 v92, v80, v81
	v_cvt_pk_bf16_f32 v93, v84, v85
	v_cvt_pk_bf16_f32 v94, v87, v94
	v_cvt_pk_bf16_f32 v95, v98, v99
	ds_read2_b64 v[96:99], v105 offset0:24 offset1:28
	s_waitcnt lgkmcnt(0)
	v_mfma_f32_16x16x32_bf16 v[60:63], v[96:99], v[92:95], v[60:63]
	ds_read2_b64 v[96:99], v104 offset0:24 offset1:28
	v_mfma_f32_16x16x32_bf16 v[56:59], v[142:145], v[138:141], v[56:59]
	v_mfma_f32_16x16x32_bf16 v[56:59], v[134:137], v[100:103], v[56:59]
	ds_read2_b64 v[100:103], v107 offset0:24 offset1:28
	s_waitcnt lgkmcnt(1)
	v_mfma_f32_16x16x32_bf16 v[96:99], v[96:99], v[92:95], v[108:111]
	s_nop 2
	ds_read2_b64 v[108:111], v106 offset0:24 offset1:28
	v_cvt_pk_bf16_f32 v84, v72, v76
	v_cvt_pk_bf16_f32 v85, v77, v75
	v_cvt_pk_bf16_f32 v86, v79, v86
	v_cvt_pk_bf16_f32 v87, v90, v91
	ds_read2_b64 v[88:91], v105 offset0:32 offset1:36
	s_waitcnt lgkmcnt(0)
	v_mfma_f32_16x16x32_bf16 v[60:63], v[88:91], v[84:87], v[60:63]
	ds_read2_b64 v[88:91], v104 offset0:32 offset1:36
	v_mfma_f32_16x16x32_bf16 v[100:103], v[100:103], v[92:95], v[130:133]
	v_mfma_f32_16x16x32_bf16 v[56:59], v[108:111], v[92:95], v[56:59]
	ds_read2_b64 v[92:95], v107 offset0:32 offset1:36
	s_waitcnt lgkmcnt(1)
	v_mfma_f32_16x16x32_bf16 v[88:91], v[88:91], v[84:87], v[96:99]
	s_nop 2
	ds_read2_b64 v[96:99], v106 offset0:32 offset1:36
	v_cvt_pk_bf16_f32 v70, v69, v70
	v_cvt_pk_bf16_f32 v71, v71, v73
	v_cvt_pk_bf16_f32 v72, v74, v78
	v_cvt_pk_bf16_f32 v73, v82, v83
	ds_read2_b64 v[74:77], v105 offset0:40 offset1:44
	s_waitcnt lgkmcnt(2)
	v_mfma_f32_16x16x32_bf16 v[92:95], v[92:95], v[84:87], v[100:103]
	ds_read2_b64 v[78:81], v107 offset0:40 offset1:44
	s_waitcnt lgkmcnt(2)
	v_mfma_f32_16x16x32_bf16 v[56:59], v[96:99], v[84:87], v[56:59]
	ds_read2_b64 v[82:85], v106 offset0:40 offset1:44
	s_waitcnt lgkmcnt(2)
	v_mfma_f32_16x16x32_bf16 v[60:63], v[74:77], v[70:73], v[60:63]
	ds_read2_b64 v[74:77], v104 offset0:40 offset1:44
	v_cvt_pk_bf16_f32 v64, v64, v65
	v_cvt_pk_bf16_f32 v65, v66, v67
	s_waitcnt lgkmcnt(0)
	v_mfma_f32_16x16x32_bf16 v[74:77], v[74:77], v[70:73], v[88:91]
	v_cvt_pk_bf16_f32 v66, v68, v53
	v_cvt_pk_bf16_f32 v67, v54, v55
	v_mfma_f32_16x16x32_bf16 v[78:81], v[78:81], v[70:73], v[92:95]
	v_mfma_f32_16x16x32_bf16 v[56:59], v[82:85], v[70:73], v[56:59]
	ds_read2_b64 v[68:71], v105 offset0:48 offset1:52
	s_waitcnt lgkmcnt(0)
	v_mfma_f32_16x16x32_bf16 v[60:63], v[68:71], v[64:67], v[60:63]
	ds_read2_b64 v[68:71], v104 offset0:48 offset1:52
	s_waitcnt lgkmcnt(0)
	v_mfma_f32_16x16x32_bf16 v[68:71], v[68:71], v[64:67], v[74:77]
	s_nop 2
	ds_read2_b64 v[72:75], v107 offset0:48 offset1:52
	s_waitcnt lgkmcnt(0)
	v_mfma_f32_16x16x32_bf16 v[72:75], v[72:75], v[64:67], v[78:81]
	s_nop 2
	ds_read2_b64 v[76:79], v106 offset0:48 offset1:52
	v_cvt_pk_bf16_f32 v46, v45, v46
	v_cvt_pk_bf16_f32 v47, v47, v48
	v_cvt_pk_bf16_f32 v48, v49, v50
	v_cvt_pk_bf16_f32 v49, v51, v52
	ds_read2_b64 v[50:53], v105 offset0:56 offset1:60
	s_waitcnt lgkmcnt(1)
	v_mfma_f32_16x16x32_bf16 v[54:57], v[76:79], v[64:67], v[56:59]
	v_div_scale_f32 v45, s[8:9], v44, v44, 1.0
	s_waitcnt lgkmcnt(0)
	v_mfma_f32_16x16x32_bf16 v[50:53], v[50:53], v[46:49], v[60:63]
	s_nop 2
	ds_read2_b64 v[58:61], v104 offset0:56 offset1:60
	s_waitcnt lgkmcnt(0)
	v_mfma_f32_16x16x32_bf16 v[58:61], v[58:61], v[46:49], v[68:71]
	ds_read2_b64 v[62:65], v107 offset0:56 offset1:60
	s_nop 1
	ds_read2_b64 v[66:69], v106 offset0:56 offset1:60
	s_waitcnt lgkmcnt(1)
	v_mfma_f32_16x16x32_bf16 v[62:65], v[62:65], v[46:49], v[72:75]
	s_waitcnt lgkmcnt(0)
	v_mfma_f32_16x16x32_bf16 v[46:49], v[66:69], v[46:49], v[54:57]
	s_nop 2
	v_rcp_f32_e32 v54, v45
	s_nop 0
	v_fma_f32 v55, -v45, v54, 1.0
	v_fmac_f32_e32 v54, v55, v54
	v_div_scale_f32 v55, vcc, 1.0, v44, 1.0
	v_mul_f32_e32 v56, v55, v54
	v_fma_f32 v57, -v45, v56, v55
	v_fmac_f32_e32 v56, v57, v54
	v_fma_f32 v45, -v45, v56, v55
	v_div_fmas_f32 v45, v45, v54, v56
	v_div_fixup_f32 v54, v45, v44, 1.0
	v_lshlrev_b64 v[44:45], 11, v[116:117]
	v_lshl_add_u64 v[44:45], s[0:1], 0, v[44:45]
	v_mul_f32_e32 v50, v54, v50
	v_mul_f32_e32 v51, v54, v51
	v_lshl_add_u64 v[44:45], v[44:45], 0, s[36:37]
	v_cvt_pk_bf16_f32 v50, v50, v51
	v_mul_f32_e32 v51, v54, v52
	v_lshl_add_u64 v[44:45], v[44:45], 0, v[2:3]
	v_mul_f32_e32 v52, v54, v53
	v_cvt_pk_bf16_f32 v51, v51, v52
	global_store_dwordx2 v[44:45], v[50:51], off offset:1536
	v_mul_f32_e32 v50, v54, v58
	v_mul_f32_e32 v51, v54, v59
	v_cvt_pk_bf16_f32 v50, v50, v51
	v_mul_f32_e32 v51, v54, v60
	v_mul_f32_e32 v52, v54, v61
	v_cvt_pk_bf16_f32 v51, v51, v52
	global_store_dwordx2 v[44:45], v[50:51], off offset:1568
	v_mul_f32_e32 v50, v54, v62
	v_mul_f32_e32 v51, v54, v63
	v_cvt_pk_bf16_f32 v50, v50, v51
	v_mul_f32_e32 v51, v54, v64
	v_mul_f32_e32 v46, v54, v46
	v_mul_f32_e32 v47, v54, v47
	v_mul_f32_e32 v52, v54, v65
	v_cvt_pk_bf16_f32 v51, v51, v52
	global_store_dwordx2 v[44:45], v[50:51], off offset:1600
	v_cvt_pk_bf16_f32 v46, v46, v47
	v_mul_f32_e32 v47, v54, v48
	v_mul_f32_e32 v48, v54, v49
	v_cvt_pk_bf16_f32 v47, v47, v48
	global_store_dwordx2 v[44:45], v[46:47], off offset:1632
	ds_read_b128 v[44:47], v128
	ds_read_b128 v[48:51], v128 offset:64
	s_waitcnt vmcnt(13) lgkmcnt(1)
	v_mfma_f32_16x16x32_bf16 v[44:47], v[44:47], v[40:43], 0
	ds_read_b128 v[52:55], v128 offset:27712
	ds_read_b128 v[56:59], v128 offset:30016
	ds_read_b128 v[108:111], v128 offset:32320
	s_waitcnt vmcnt(12) lgkmcnt(3)
	v_mfma_f32_16x16x32_bf16 v[100:103], v[48:51], v[36:39], v[44:47]
	ds_read_b128 v[48:51], v128 offset:2368
	s_nop 1
	ds_read_b128 v[44:47], v128 offset:2304
	s_waitcnt lgkmcnt(0)
	v_mfma_f32_16x16x32_bf16 v[44:47], v[44:47], v[40:43], 0
	v_mfma_f32_16x16x32_bf16 v[96:99], v[48:51], v[36:39], v[44:47]
	ds_read_b128 v[48:51], v128 offset:4672
	s_nop 5
	ds_read_b128 v[44:47], v128 offset:4608
	s_waitcnt lgkmcnt(0)
	v_mfma_f32_16x16x32_bf16 v[44:47], v[44:47], v[40:43], 0
	v_mfma_f32_16x16x32_bf16 v[92:95], v[48:51], v[36:39], v[44:47]
	ds_read_b128 v[48:51], v128 offset:6976
	s_nop 5
	ds_read_b128 v[44:47], v128 offset:6912
	s_waitcnt lgkmcnt(0)
	v_mfma_f32_16x16x32_bf16 v[44:47], v[44:47], v[40:43], 0
	v_mfma_f32_16x16x32_bf16 v[88:91], v[48:51], v[36:39], v[44:47]
	ds_read_b128 v[48:51], v128 offset:9280
	s_nop 5
	ds_read_b128 v[44:47], v128 offset:9216
	s_waitcnt lgkmcnt(0)
	v_mfma_f32_16x16x32_bf16 v[44:47], v[44:47], v[40:43], 0
	v_mfma_f32_16x16x32_bf16 v[84:87], v[48:51], v[36:39], v[44:47]
	ds_read_b128 v[48:51], v128 offset:11584
	s_nop 5
	ds_read_b128 v[44:47], v128 offset:11520
	s_waitcnt lgkmcnt(0)
	v_mfma_f32_16x16x32_bf16 v[44:47], v[44:47], v[40:43], 0
	v_mfma_f32_16x16x32_bf16 v[80:83], v[48:51], v[36:39], v[44:47]
	ds_read_b128 v[48:51], v128 offset:13888
	s_nop 5
	ds_read_b128 v[44:47], v128 offset:13824
	s_waitcnt lgkmcnt(0)
	v_mfma_f32_16x16x32_bf16 v[44:47], v[44:47], v[40:43], 0
	v_mfma_f32_16x16x32_bf16 v[76:79], v[48:51], v[36:39], v[44:47]
	ds_read_b128 v[48:51], v128 offset:16192
	s_nop 5
	ds_read_b128 v[44:47], v128 offset:16128
	s_waitcnt lgkmcnt(0)
	v_mfma_f32_16x16x32_bf16 v[44:47], v[44:47], v[40:43], 0
	v_mfma_f32_16x16x32_bf16 v[72:75], v[48:51], v[36:39], v[44:47]
	ds_read_b128 v[48:51], v128 offset:18496
	s_nop 5
	ds_read_b128 v[44:47], v128 offset:18432
	s_waitcnt lgkmcnt(0)
	v_mfma_f32_16x16x32_bf16 v[44:47], v[44:47], v[40:43], 0
	v_mfma_f32_16x16x32_bf16 v[68:71], v[48:51], v[36:39], v[44:47]
	ds_read_b128 v[48:51], v128 offset:20800
	s_nop 5
	ds_read_b128 v[44:47], v128 offset:20736
	s_waitcnt lgkmcnt(0)
	v_mfma_f32_16x16x32_bf16 v[44:47], v[44:47], v[40:43], 0
	v_mfma_f32_16x16x32_bf16 v[64:67], v[48:51], v[36:39], v[44:47]
	ds_read_b128 v[48:51], v128 offset:23104
	s_nop 5
	ds_read_b128 v[44:47], v128 offset:23040
	s_waitcnt lgkmcnt(0)
	v_mfma_f32_16x16x32_bf16 v[44:47], v[44:47], v[40:43], 0
	v_mfma_f32_16x16x32_bf16 v[60:63], v[48:51], v[36:39], v[44:47]
	ds_read_b128 v[48:51], v128 offset:25408
	s_nop 5
	ds_read_b128 v[44:47], v128 offset:25344
	s_waitcnt lgkmcnt(0)
	v_mfma_f32_16x16x32_bf16 v[44:47], v[44:47], v[40:43], 0
	v_mfma_f32_16x16x32_bf16 v[44:47], v[48:51], v[36:39], v[44:47]
	ds_read_b128 v[48:51], v128 offset:27648
	s_waitcnt lgkmcnt(0)
	v_mfma_f32_16x16x32_bf16 v[48:51], v[48:51], v[40:43], 0
	v_mfma_f32_16x16x32_bf16 v[48:51], v[52:55], v[36:39], v[48:51]
	ds_read_b128 v[52:55], v128 offset:29952
	s_waitcnt lgkmcnt(0)
	v_mfma_f32_16x16x32_bf16 v[52:55], v[52:55], v[40:43], 0
	v_mfma_f32_16x16x32_bf16 v[52:55], v[56:59], v[36:39], v[52:55]
	ds_read_b128 v[56:59], v128 offset:32256
	s_waitcnt lgkmcnt(0)
	v_mfma_f32_16x16x32_bf16 v[56:59], v[56:59], v[40:43], 0
	v_mfma_f32_16x16x32_bf16 v[56:59], v[108:111], v[36:39], v[56:59]
	ds_read_b128 v[108:111], v128 offset:34560
	s_waitcnt lgkmcnt(0)
	v_mfma_f32_16x16x32_bf16 v[40:43], v[108:111], v[40:43], 0
	ds_read_b128 v[108:111], v128 offset:34624
	s_waitcnt lgkmcnt(0)
	v_mfma_f32_16x16x32_bf16 v[36:39], v[108:111], v[36:39], v[40:43]
	s_nop 4
	v_max_f32_e32 v40, v101, v101
	v_max_f32_e32 v41, v100, v100
	v_max_f32_e32 v40, v41, v40
	v_max_f32_e32 v41, v103, v103
	v_max_f32_e32 v42, v102, v102
	v_max_f32_e32 v41, v42, v41
	v_max3_f32 v40, v40, v41, s13
	v_max_f32_e32 v41, v97, v97
	v_max_f32_e32 v42, v96, v96
	v_max_f32_e32 v41, v42, v41
	v_max_f32_e32 v42, v99, v99
	v_max_f32_e32 v43, v98, v98
	v_max_f32_e32 v42, v43, v42
	v_max3_f32 v40, v41, v42, v40
	v_max_f32_e32 v41, v93, v93
	v_max_f32_e32 v42, v92, v92
	v_max_f32_e32 v41, v42, v41
	v_max_f32_e32 v42, v95, v95
	v_max_f32_e32 v43, v94, v94
	v_max_f32_e32 v42, v43, v42
	v_max3_f32 v40, v41, v42, v40
	v_max_f32_e32 v41, v89, v89
	v_max_f32_e32 v42, v88, v88
	v_max_f32_e32 v41, v42, v41
	v_max_f32_e32 v42, v91, v91
	v_max_f32_e32 v43, v90, v90
	v_max_f32_e32 v42, v43, v42
	v_max3_f32 v40, v41, v42, v40
	v_max_f32_e32 v41, v85, v85
	v_max_f32_e32 v42, v84, v84
	v_max_f32_e32 v41, v42, v41
	v_max_f32_e32 v42, v87, v87
	v_max_f32_e32 v43, v86, v86
	v_max_f32_e32 v42, v43, v42
	v_max3_f32 v40, v41, v42, v40
	v_max_f32_e32 v41, v81, v81
	v_max_f32_e32 v42, v80, v80
	v_max_f32_e32 v41, v42, v41
	v_max_f32_e32 v42, v83, v83
	v_max_f32_e32 v43, v82, v82
	v_max_f32_e32 v42, v43, v42
	v_max3_f32 v40, v41, v42, v40
	v_max_f32_e32 v41, v77, v77
	v_max_f32_e32 v42, v76, v76
	v_max_f32_e32 v41, v42, v41
	v_max_f32_e32 v42, v79, v79
	v_max_f32_e32 v43, v78, v78
	v_max_f32_e32 v42, v43, v42
	v_max3_f32 v40, v41, v42, v40
	v_max_f32_e32 v41, v73, v73
	v_max_f32_e32 v42, v72, v72
	v_max_f32_e32 v41, v42, v41
	v_max_f32_e32 v42, v75, v75
	v_max_f32_e32 v43, v74, v74
	v_max_f32_e32 v42, v43, v42
	v_max3_f32 v40, v41, v42, v40
	v_max_f32_e32 v41, v69, v69
	v_max_f32_e32 v42, v68, v68
	v_max_f32_e32 v41, v42, v41
	v_max_f32_e32 v42, v71, v71
	v_max_f32_e32 v43, v70, v70
	v_max_f32_e32 v42, v43, v42
	v_max3_f32 v40, v41, v42, v40
	v_max_f32_e32 v41, v65, v65
	v_max_f32_e32 v42, v64, v64
	v_max_f32_e32 v41, v42, v41
	v_max_f32_e32 v42, v67, v67
	v_max_f32_e32 v43, v66, v66
	v_max_f32_e32 v42, v43, v42
	v_max3_f32 v40, v41, v42, v40
	v_max_f32_e32 v41, v61, v61
	v_max_f32_e32 v42, v60, v60
	v_max_f32_e32 v41, v42, v41
	v_max_f32_e32 v42, v63, v63
	v_max_f32_e32 v43, v62, v62
	v_max_f32_e32 v42, v43, v42
	v_max3_f32 v40, v41, v42, v40
	v_max_f32_e32 v41, v45, v45
	v_max_f32_e32 v42, v44, v44
	v_max_f32_e32 v41, v42, v41
	v_max_f32_e32 v42, v47, v47
	v_max_f32_e32 v43, v46, v46
	v_max_f32_e32 v42, v43, v42
	v_max3_f32 v40, v41, v42, v40
	v_max_f32_e32 v41, v49, v49
	v_max_f32_e32 v42, v48, v48
	v_max_f32_e32 v41, v42, v41
	v_max_f32_e32 v42, v51, v51
	v_max_f32_e32 v43, v50, v50
	v_max_f32_e32 v42, v43, v42
	v_max3_f32 v40, v41, v42, v40
	v_max_f32_e32 v41, v53, v53
	v_max_f32_e32 v42, v52, v52
	v_max_f32_e32 v41, v42, v41
	v_max_f32_e32 v42, v55, v55
	v_max_f32_e32 v43, v54, v54
	v_max_f32_e32 v42, v43, v42
	v_max3_f32 v40, v41, v42, v40
	v_max_f32_e32 v41, v57, v57
	v_max_f32_e32 v42, v56, v56
	v_max_f32_e32 v41, v42, v41
	v_max_f32_e32 v42, v59, v59
	v_max_f32_e32 v43, v58, v58
	v_max_f32_e32 v42, v43, v42
	v_max3_f32 v40, v41, v42, v40
	v_max_f32_e32 v41, v37, v37
	v_max_f32_e32 v42, v36, v36
	v_max_f32_e32 v41, v42, v41
	v_max_f32_e32 v42, v39, v39
	v_max_f32_e32 v43, v38, v38
	v_max_f32_e32 v42, v43, v42
	v_max3_f32 v40, v41, v42, v40
	ds_bpermute_b32 v41, v126, v40
	s_mov_b32 s13, s12
	s_waitcnt lgkmcnt(0)
	v_max_f32_e32 v41, v41, v41
	v_max_f32_e32 v40, v40, v41
	ds_bpermute_b32 v41, v127, v40
	s_waitcnt lgkmcnt(0)
	v_max_f32_e32 v41, v41, v41
	v_max_f32_e32 v113, v40, v41
	v_sub_f32_e32 v40, v100, v113
	v_exp_f32_e32 v100, v40
	v_sub_f32_e32 v41, v101, v113
	v_exp_f32_e32 v101, v41
	v_sub_f32_e32 v41, v102, v113
	v_exp_f32_e32 v102, v41
	v_sub_f32_e32 v41, v103, v113
	v_exp_f32_e32 v103, v41
	v_sub_f32_e32 v41, v96, v113
	v_add_f32_e32 v40, 0, v100
	v_exp_f32_e32 v108, v41
	v_sub_f32_e32 v41, v97, v113
	v_add_f32_e32 v40, v101, v40
	v_exp_f32_e32 v109, v41
	v_sub_f32_e32 v41, v98, v113
	v_add_f32_e32 v40, v102, v40
	v_exp_f32_e32 v110, v41
	v_sub_f32_e32 v41, v99, v113
	v_add_f32_e32 v40, v103, v40
	v_exp_f32_e32 v111, v41
	v_sub_f32_e32 v41, v92, v113
	v_add_f32_e32 v40, v108, v40
	v_exp_f32_e32 v92, v41
	v_sub_f32_e32 v41, v93, v113
	v_add_f32_e32 v40, v109, v40
	v_exp_f32_e32 v93, v41
	v_sub_f32_e32 v41, v94, v113
	v_add_f32_e32 v40, v110, v40
	v_exp_f32_e32 v94, v41
	v_sub_f32_e32 v41, v95, v113
	v_add_f32_e32 v40, v111, v40
	v_exp_f32_e32 v95, v41
	v_sub_f32_e32 v41, v88, v113
	v_add_f32_e32 v40, v92, v40
	v_exp_f32_e32 v96, v41
	v_sub_f32_e32 v41, v89, v113
	v_add_f32_e32 v40, v93, v40
	v_exp_f32_e32 v97, v41
	v_sub_f32_e32 v41, v90, v113
	v_add_f32_e32 v40, v94, v40
	v_exp_f32_e32 v98, v41
	v_sub_f32_e32 v41, v91, v113
	v_add_f32_e32 v40, v95, v40
	v_exp_f32_e32 v99, v41
	v_sub_f32_e32 v41, v84, v113
	v_add_f32_e32 v40, v96, v40
	v_exp_f32_e32 v84, v41
	v_sub_f32_e32 v41, v85, v113
	v_add_f32_e32 v40, v97, v40
	v_exp_f32_e32 v85, v41
	v_sub_f32_e32 v41, v86, v113
	v_add_f32_e32 v40, v98, v40
	v_exp_f32_e32 v86, v41
	v_sub_f32_e32 v41, v87, v113
	v_add_f32_e32 v40, v99, v40
	v_exp_f32_e32 v87, v41
	v_sub_f32_e32 v41, v80, v113
	v_add_f32_e32 v40, v84, v40
	v_exp_f32_e32 v88, v41
	v_sub_f32_e32 v41, v81, v113
	v_add_f32_e32 v40, v85, v40
	v_exp_f32_e32 v89, v41
	v_sub_f32_e32 v41, v82, v113
	v_add_f32_e32 v40, v86, v40
	v_exp_f32_e32 v90, v41
	v_sub_f32_e32 v41, v83, v113
	v_add_f32_e32 v40, v87, v40
	v_exp_f32_e32 v91, v41
	v_sub_f32_e32 v41, v76, v113
	v_add_f32_e32 v40, v88, v40
	v_exp_f32_e32 v76, v41
	v_sub_f32_e32 v41, v77, v113
	v_add_f32_e32 v40, v89, v40
	v_exp_f32_e32 v77, v41
	v_sub_f32_e32 v41, v78, v113
	v_add_f32_e32 v40, v90, v40
	v_exp_f32_e32 v78, v41
	v_sub_f32_e32 v41, v79, v113
	v_add_f32_e32 v40, v91, v40
	v_exp_f32_e32 v79, v41
	v_sub_f32_e32 v41, v72, v113
	v_add_f32_e32 v40, v76, v40
	v_exp_f32_e32 v80, v41
	v_sub_f32_e32 v41, v73, v113
	v_add_f32_e32 v40, v77, v40
	v_exp_f32_e32 v81, v41
	v_sub_f32_e32 v41, v74, v113
	v_add_f32_e32 v40, v78, v40
	v_exp_f32_e32 v82, v41
	v_sub_f32_e32 v41, v75, v113
	v_add_f32_e32 v40, v79, v40
	v_exp_f32_e32 v83, v41
	v_sub_f32_e32 v41, v68, v113
	v_add_f32_e32 v40, v80, v40
	v_exp_f32_e32 v68, v41
	v_sub_f32_e32 v41, v69, v113
	v_add_f32_e32 v40, v81, v40
	v_exp_f32_e32 v69, v41
	v_sub_f32_e32 v41, v70, v113
	v_add_f32_e32 v40, v82, v40
	v_exp_f32_e32 v70, v41
	v_sub_f32_e32 v41, v71, v113
	v_add_f32_e32 v40, v83, v40
	v_exp_f32_e32 v71, v41
	v_sub_f32_e32 v41, v64, v113
	v_add_f32_e32 v40, v68, v40
	v_exp_f32_e32 v72, v41
	v_sub_f32_e32 v41, v65, v113
	v_add_f32_e32 v40, v69, v40
	v_exp_f32_e32 v73, v41
	v_sub_f32_e32 v41, v66, v113
	v_add_f32_e32 v40, v70, v40
	v_exp_f32_e32 v74, v41
	v_sub_f32_e32 v41, v67, v113
	v_add_f32_e32 v40, v71, v40
	v_exp_f32_e32 v75, v41
	v_sub_f32_e32 v41, v60, v113
	v_add_f32_e32 v40, v72, v40
	v_exp_f32_e32 v60, v41
	v_sub_f32_e32 v41, v61, v113
	v_add_f32_e32 v40, v73, v40
	v_exp_f32_e32 v61, v41
	v_sub_f32_e32 v41, v62, v113
	v_add_f32_e32 v40, v74, v40
	v_exp_f32_e32 v62, v41
	v_sub_f32_e32 v41, v63, v113
	v_add_f32_e32 v40, v75, v40
	v_exp_f32_e32 v63, v41
	v_sub_f32_e32 v41, v44, v113
	v_add_f32_e32 v40, v60, v40
	v_exp_f32_e32 v64, v41
	v_sub_f32_e32 v41, v45, v113
	v_add_f32_e32 v40, v61, v40
	v_exp_f32_e32 v65, v41
	v_sub_f32_e32 v41, v46, v113
	v_add_f32_e32 v40, v62, v40
	v_exp_f32_e32 v66, v41
	v_sub_f32_e32 v41, v47, v113
	v_add_f32_e32 v40, v63, v40
	v_exp_f32_e32 v67, v41
	v_sub_f32_e32 v41, v48, v113
	v_add_f32_e32 v40, v64, v40
	v_exp_f32_e32 v45, v41
	v_sub_f32_e32 v41, v49, v113
	v_add_f32_e32 v40, v65, v40
	v_exp_f32_e32 v46, v41
	v_sub_f32_e32 v41, v50, v113
	v_add_f32_e32 v40, v66, v40
	v_exp_f32_e32 v47, v41
	v_sub_f32_e32 v41, v51, v113
	v_add_f32_e32 v40, v67, v40
	v_exp_f32_e32 v48, v41
	v_sub_f32_e32 v41, v52, v113
	v_add_f32_e32 v40, v45, v40
	v_exp_f32_e32 v49, v41
	v_sub_f32_e32 v41, v53, v113
	v_add_f32_e32 v40, v46, v40
	v_exp_f32_e32 v50, v41
	v_sub_f32_e32 v41, v54, v113
	v_add_f32_e32 v40, v47, v40
	v_exp_f32_e32 v51, v41
	v_sub_f32_e32 v41, v55, v113
	v_add_f32_e32 v40, v48, v40
	v_exp_f32_e32 v52, v41
	v_add_f32_e32 v40, v49, v40
	v_add_f32_e32 v40, v50, v40
	v_add_f32_e32 v40, v51, v40
	v_add_f32_e32 v41, v52, v40
	v_sub_f32_e32 v40, v56, v113
	v_exp_f32_e32 v40, v40
	v_cvt_pk_bf16_f32 v54, v100, v101
	v_cvt_pk_bf16_f32 v55, v102, v103
	v_cvt_pk_bf16_f32 v56, v108, v109
	v_sub_f32_e32 v36, v36, v113
	v_add_f32_e32 v42, v40, v41
	v_sub_f32_e32 v41, v57, v113
	v_cvt_pk_bf16_f32 v57, v110, v111
	ds_read2_b64 v[100:103], v105 offset1:4
	ds_read2_b64 v[108:111], v104 offset1:4
	ds_read2_b64 v[130:133], v107 offset1:4
	ds_read2_b64 v[134:137], v106 offset1:4
	v_cvt_pk_bf16_f32 v92, v92, v93
	v_cvt_pk_bf16_f32 v93, v94, v95
	v_cvt_pk_bf16_f32 v94, v96, v97
	v_cvt_pk_bf16_f32 v95, v98, v99
	ds_read2_b64 v[96:99], v105 offset0:8 offset1:12
	s_waitcnt lgkmcnt(4)
	v_mfma_f32_16x16x32_bf16 v[100:103], v[100:103], v[54:57], 0
	v_exp_f32_e32 v41, v41
	v_sub_f32_e32 v37, v37, v113
	v_exp_f32_e32 v37, v37
	s_waitcnt lgkmcnt(0)
	v_mfma_f32_16x16x32_bf16 v[96:99], v[96:99], v[92:95], v[100:103]
	s_nop 2
	ds_read2_b64 v[100:103], v104 offset0:8 offset1:12
	v_add_f32_e32 v43, v41, v42
	v_sub_f32_e32 v42, v58, v113
	v_mfma_f32_16x16x32_bf16 v[108:111], v[108:111], v[54:57], 0
	v_exp_f32_e32 v42, v42
	v_sub_f32_e32 v38, v38, v113
	v_exp_f32_e32 v38, v38
	s_waitcnt lgkmcnt(0)
	v_mfma_f32_16x16x32_bf16 v[100:103], v[100:103], v[92:95], v[108:111]
	v_add_f32_e32 v44, v42, v43
	s_nop 1
	ds_read2_b64 v[108:111], v107 offset0:8 offset1:12
	v_sub_f32_e32 v43, v59, v113
	v_mfma_f32_16x16x32_bf16 v[130:133], v[130:133], v[54:57], 0
	v_exp_f32_e32 v43, v43
	v_sub_f32_e32 v39, v39, v113
	v_exp_f32_e32 v39, v39
	s_waitcnt lgkmcnt(0)
	v_mfma_f32_16x16x32_bf16 v[108:111], v[108:111], v[92:95], v[130:133]
	v_add_f32_e32 v53, v43, v44
	s_nop 1
	ds_read2_b64 v[130:133], v106 offset0:8 offset1:12
	v_cvt_pk_bf16_f32 v84, v84, v85
	v_mfma_f32_16x16x32_bf16 v[54:57], v[134:137], v[54:57], 0
	v_cvt_pk_bf16_f32 v85, v86, v87
	v_cvt_pk_bf16_f32 v86, v88, v89
	v_cvt_pk_bf16_f32 v87, v90, v91
	s_waitcnt lgkmcnt(0)
	v_mfma_f32_16x16x32_bf16 v[54:57], v[130:133], v[92:95], v[54:57]
	ds_read2_b64 v[88:91], v105 offset0:16 offset1:20
	ds_read2_b64 v[92:95], v104 offset0:16 offset1:20
	v_exp_f32_e32 v44, v36
	s_waitcnt lgkmcnt(1)
	v_mfma_f32_16x16x32_bf16 v[88:91], v[88:91], v[84:87], v[96:99]
	s_nop 2
	ds_read2_b64 v[96:99], v107 offset0:16 offset1:20
	v_add_f32_e32 v36, v44, v53
	v_add_f32_e32 v36, v37, v36
	s_waitcnt lgkmcnt(1)
	v_mfma_f32_16x16x32_bf16 v[92:95], v[92:95], v[84:87], v[100:103]
	v_add_f32_e32 v36, v38, v36
	v_add_f32_e32 v36, v39, v36
	ds_bpermute_b32 v53, v126, v36
	ds_read2_b64 v[100:103], v106 offset0:16 offset1:20
	s_waitcnt lgkmcnt(2)
	v_mfma_f32_16x16x32_bf16 v[96:99], v[96:99], v[84:87], v[108:111]
	v_cvt_pk_bf16_f32 v76, v76, v77
	v_cvt_pk_bf16_f32 v77, v78, v79
	v_cvt_pk_bf16_f32 v78, v80, v81
	s_waitcnt lgkmcnt(0)
	v_mfma_f32_16x16x32_bf16 v[54:57], v[100:103], v[84:87], v[54:57]
	v_cvt_pk_bf16_f32 v79, v82, v83
	ds_read2_b64 v[80:83], v105 offset0:24 offset1:28
	ds_read2_b64 v[84:87], v104 offset0:24 offset1:28
	s_waitcnt lgkmcnt(1)
	v_mfma_f32_16x16x32_bf16 v[80:83], v[80:83], v[76:79], v[88:91]
	s_nop 2
	ds_read2_b64 v[88:91], v107 offset0:24 offset1:28
	v_add_f32_e32 v36, v36, v53
	ds_bpermute_b32 v53, v127, v36
	s_waitcnt lgkmcnt(2)
	v_mfma_f32_16x16x32_bf16 v[84:87], v[84:87], v[76:79], v[92:95]
	s_waitcnt lgkmcnt(0)
	v_add_f32_e32 v36, v36, v53
	s_nop 0
	ds_read2_b64 v[92:95], v106 offset0:24 offset1:28
	v_mfma_f32_16x16x32_bf16 v[88:91], v[88:91], v[76:79], v[96:99]
	v_cvt_pk_bf16_f32 v68, v68, v69
	v_cvt_pk_bf16_f32 v69, v70, v71
	v_cvt_pk_bf16_f32 v70, v72, v73
	s_waitcnt lgkmcnt(0)
	v_mfma_f32_16x16x32_bf16 v[54:57], v[92:95], v[76:79], v[54:57]
	v_cvt_pk_bf16_f32 v71, v74, v75
	ds_read2_b64 v[72:75], v105 offset0:32 offset1:36
	ds_read2_b64 v[76:79], v104 offset0:32 offset1:36
	s_waitcnt lgkmcnt(1)
	v_mfma_f32_16x16x32_bf16 v[72:75], v[72:75], v[68:71], v[80:83]
	s_nop 2
	ds_read2_b64 v[80:83], v107 offset0:32 offset1:36
	s_waitcnt lgkmcnt(1)
	v_mfma_f32_16x16x32_bf16 v[76:79], v[76:79], v[68:71], v[84:87]
	s_nop 2
	ds_read2_b64 v[84:87], v106 offset0:32 offset1:36
	s_waitcnt lgkmcnt(1)
	v_mfma_f32_16x16x32_bf16 v[80:83], v[80:83], v[68:71], v[88:91]
	v_cvt_pk_bf16_f32 v58, v60, v61
	v_cvt_pk_bf16_f32 v59, v62, v63
	v_cvt_pk_bf16_f32 v60, v64, v65
	s_waitcnt lgkmcnt(0)
	v_mfma_f32_16x16x32_bf16 v[54:57], v[84:87], v[68:71], v[54:57]
	v_cvt_pk_bf16_f32 v61, v66, v67
	ds_read2_b64 v[62:65], v105 offset0:40 offset1:44
	ds_read2_b64 v[66:69], v104 offset0:40 offset1:44
	s_waitcnt lgkmcnt(1)
	v_mfma_f32_16x16x32_bf16 v[62:65], v[62:65], v[58:61], v[72:75]
	s_nop 2
	ds_read2_b64 v[70:73], v107 offset0:40 offset1:44
	s_waitcnt lgkmcnt(1)
	v_mfma_f32_16x16x32_bf16 v[66:69], v[66:69], v[58:61], v[76:79]
	s_nop 2
	ds_read2_b64 v[74:77], v106 offset0:40 offset1:44
	s_waitcnt lgkmcnt(1)
	v_mfma_f32_16x16x32_bf16 v[70:73], v[70:73], v[58:61], v[80:83]
	v_cvt_pk_bf16_f32 v46, v45, v46
	v_cvt_pk_bf16_f32 v47, v47, v48
	v_cvt_pk_bf16_f32 v48, v49, v50
	s_waitcnt lgkmcnt(0)
	v_mfma_f32_16x16x32_bf16 v[54:57], v[74:77], v[58:61], v[54:57]
	v_cvt_pk_bf16_f32 v49, v51, v52
	ds_read2_b64 v[50:53], v105 offset0:48 offset1:52
	ds_read2_b64 v[58:61], v104 offset0:48 offset1:52
	s_waitcnt lgkmcnt(1)
	v_mfma_f32_16x16x32_bf16 v[50:53], v[50:53], v[46:49], v[62:65]
	s_nop 2
	ds_read2_b64 v[62:65], v107 offset0:48 offset1:52
	s_waitcnt lgkmcnt(1)
	v_mfma_f32_16x16x32_bf16 v[58:61], v[58:61], v[46:49], v[66:69]
	s_nop 2
	ds_read2_b64 v[66:69], v106 offset0:48 offset1:52
	s_waitcnt lgkmcnt(1)
	v_mfma_f32_16x16x32_bf16 v[62:65], v[62:65], v[46:49], v[70:73]
	v_cvt_pk_bf16_f32 v40, v40, v41
	v_cvt_pk_bf16_f32 v41, v42, v43
	v_cvt_pk_bf16_f32 v42, v44, v37
	s_waitcnt lgkmcnt(0)
	v_mfma_f32_16x16x32_bf16 v[46:49], v[66:69], v[46:49], v[54:57]
	v_cvt_pk_bf16_f32 v43, v38, v39
	s_nop 2
	ds_read2_b64 v[54:57], v105 offset0:56 offset1:60
	v_div_scale_f32 v37, s[8:9], v36, v36, 1.0
	s_waitcnt lgkmcnt(0)
	v_mfma_f32_16x16x32_bf16 v[50:53], v[54:57], v[40:43], v[50:53]
	ds_read2_b64 v[54:57], v104 offset0:56 offset1:60
	v_readlane_b32 s8, v243, 33
	s_add_i32 s10, s10, s8
	s_waitcnt lgkmcnt(0)
	v_mfma_f32_16x16x32_bf16 v[54:57], v[54:57], v[40:43], v[58:61]
	s_nop 2
	ds_read2_b64 v[58:61], v107 offset0:56 offset1:60
	s_waitcnt lgkmcnt(0)
	v_mfma_f32_16x16x32_bf16 v[58:61], v[58:61], v[40:43], v[62:65]
	s_nop 2
	ds_read2_b64 v[62:65], v106 offset0:56 offset1:60
	s_waitcnt lgkmcnt(0)
	v_mfma_f32_16x16x32_bf16 v[38:41], v[62:65], v[40:43], v[46:49]
	v_rcp_f32_e32 v42, v37
	s_nop 0
	v_fma_f32 v43, -v37, v42, 1.0
	v_fmac_f32_e32 v42, v43, v42
	v_div_scale_f32 v43, vcc, 1.0, v36, 1.0
	v_mul_f32_e32 v44, v43, v42
	v_fma_f32 v45, -v37, v44, v43
	v_fmac_f32_e32 v44, v45, v42
	v_fma_f32 v37, -v37, v44, v43
	v_div_fmas_f32 v37, v37, v42, v44
	v_div_fixup_f32 v44, v37, v36, 1.0
	v_lshlrev_b64 v[36:37], 11, v[114:115]
	v_lshl_add_u64 v[36:37], s[0:1], 0, v[36:37]
	v_mul_f32_e32 v42, v44, v50
	v_mul_f32_e32 v43, v44, v51
	v_lshl_add_u64 v[36:37], v[36:37], 0, s[36:37]
	v_cvt_pk_bf16_f32 v42, v42, v43
	v_mul_f32_e32 v43, v44, v52
	v_lshl_add_u64 v[36:37], v[36:37], 0, v[2:3]
	v_mul_f32_e32 v45, v44, v53
	v_cvt_pk_bf16_f32 v43, v43, v45
	global_store_dwordx2 v[36:37], v[42:43], off offset:1536
	v_mul_f32_e32 v42, v44, v54
	v_mul_f32_e32 v43, v44, v55
	v_cvt_pk_bf16_f32 v42, v42, v43
	v_mul_f32_e32 v43, v44, v56
	v_mul_f32_e32 v45, v44, v57
	v_cvt_pk_bf16_f32 v43, v43, v45
	global_store_dwordx2 v[36:37], v[42:43], off offset:1568
	v_mul_f32_e32 v42, v44, v58
	v_mul_f32_e32 v43, v44, v59
	v_cvt_pk_bf16_f32 v42, v42, v43
	v_mul_f32_e32 v43, v44, v60
	v_mul_f32_e32 v38, v44, v38
	v_mul_f32_e32 v39, v44, v39
	v_mul_f32_e32 v45, v44, v61
	v_cvt_pk_bf16_f32 v43, v43, v45
	global_store_dwordx2 v[36:37], v[42:43], off offset:1600
	v_cvt_pk_bf16_f32 v38, v38, v39
	v_mul_f32_e32 v39, v44, v40
	s_andn2_b64 vcc, exec, s[6:7]
	v_mul_f32_e32 v40, v44, v41
	v_cvt_pk_bf16_f32 v39, v39, v40
	global_store_dwordx2 v[36:37], v[38:39], off offset:1632
	s_barrier
	s_cbranch_vccz .LBB0_582
.LBB0_578:
	s_and_b32 s6, s13, 0xffffff00
	v_add_u32_e32 v116, s6, v120
	s_and_b32 s6, s13, 0xc0
	s_lshl_b32 s36, s6, 1
	v_ashrrev_i32_e32 v117, 31, v116
	v_lshl_add_u64 v[36:37], v[0:1], 0, s[36:37]
	v_lshlrev_b64 v[38:39], 9, v[116:117]
	v_or_b32_e32 v114, 16, v116
	v_lshl_add_u64 v[38:39], v[36:37], 0, v[38:39]
	v_ashrrev_i32_e32 v115, 31, v114
	s_waitcnt vmcnt(0)
	global_load_dwordx4 v[108:111], v[38:39], off
	global_load_dwordx4 v[60:63], v[38:39], off offset:64
	v_lshlrev_b64 v[38:39], 9, v[114:115]
	v_lshl_add_u64 v[36:37], v[36:37], 0, v[38:39]
	global_load_dwordx4 v[40:43], v[36:37], off
	s_nop 0
	global_load_dwordx4 v[36:39], v[36:37], off offset:64
	ds_write_b128 v119, v[16:19]
	ds_write_b128 v119, v[12:15] offset:16
	ds_write_b128 v119, v[8:11] offset:32
	ds_write_b128 v119, v[4:7] offset:48
	ds_write_b16 v121, v20 offset:36864
	ds_write_b16_d16_hi v121, v20 offset:37392
	ds_write_b16 v121, v21 offset:37920
	ds_write_b16_d16_hi v121, v21 offset:38448
	ds_write_b16 v121, v22 offset:38976
	ds_write_b16_d16_hi v121, v22 offset:39504
	ds_write_b16 v121, v23 offset:40032
	ds_write_b16_d16_hi v121, v23 offset:40560
	ds_write_b16 v121, v24 offset:41088
	ds_write_b16_d16_hi v121, v24 offset:41616
	ds_write_b16 v121, v25 offset:42144
	ds_write_b16_d16_hi v121, v25 offset:42672
	ds_write_b16 v121, v26 offset:43200
	ds_write_b16_d16_hi v121, v26 offset:43728
	ds_write_b16 v121, v27 offset:44256
	ds_write_b16_d16_hi v121, v27 offset:44784
	ds_write_b16 v121, v28 offset:45312
	ds_write_b16_d16_hi v121, v28 offset:45840
	ds_write_b16 v121, v29 offset:46368
	ds_write_b16_d16_hi v121, v29 offset:46896
	ds_write_b16 v121, v30 offset:47424
	ds_write_b16_d16_hi v121, v30 offset:47952
	ds_write_b16 v121, v31 offset:48480
	ds_write_b16_d16_hi v121, v31 offset:49008
	ds_write_b16 v121, v32 offset:49536
	ds_write_b16_d16_hi v121, v32 offset:50064
	ds_write_b16 v121, v33 offset:50592
	ds_write_b16_d16_hi v121, v33 offset:51120
	ds_write_b16 v121, v34 offset:51648
	ds_write_b16_d16_hi v121, v34 offset:52176
	ds_write_b16 v121, v35 offset:52704
	ds_write_b16_d16_hi v121, v35 offset:53232
	s_waitcnt lgkmcnt(0)
	s_barrier
	s_add_i32 s11, s11, s92
	s_cmpk_gt_i32 s11, 0x1ff
	s_cselect_b64 s[6:7], -1, 0
	s_cmpk_lt_i32 s11, 0x200
	s_mov_b64 s[8:9], -1
	s_cbranch_scc1 .LBB0_580
	v_readlane_b32 s8, v243, 37
	s_add_i32 s12, s13, s8
	global_load_dwordx4 v[4:7], v[0:1], off
	global_load_dwordx4 v[8:11], v[0:1], off
	global_load_dwordx4 v[12:15], v[0:1], off
	global_load_dwordx4 v[16:19], v[0:1], off
	global_load_dwordx4 v[20:23], v[0:1], off
	global_load_dwordx4 v[24:27], v[0:1], off
	global_load_dwordx4 v[28:31], v[0:1], off
	global_load_dwordx4 v[32:35], v[0:1], off
	s_mov_b64 s[8:9], 0
